# P10 traverses row tiles in reverse (last-written act rows first, Infinity Cache hits) on top of v6
# speedup vs baseline: 1.0052x; 1.0052x over previous
; #define LAS __attribute__((address_space(3)))
; #define PG8_BAR __builtin_amdgcn_s_barrier()
;     __device__ bool next(int i, Unit& u) const {
;     ...
;         int wgid = (int)L; { const int q = nwg / NXCD, r = nwg % NXCD, xcd = wgid % NXCD, off = wgid / NXCD; wgid = (xcd < r ? xcd * (q + 1) : r * (q + 1) + (xcd - r) * q) + off; }
;         const int nig = WGM * nN, gid = wgid / nig, fm = gid * WGM, gsz = (nM - fm) < WGM ? (nM - fm) : WGM;
;         const int pm = fm + ((wgid % nig) % gsz), pn = (wgid % nig) / gsz;
;         u.pm = pm; u.pn = pn;
;         if (mode == 0) { u.aoff = (size_t)pm * 256 * lda2; u.boff = (size_t)pn * 256 * ldb2; }
;         else if (mode == 3) { const int b = pm >> 2, h = pm & 3; u.aoff = (size_t)(b * 256) * lda2 + (size_t)h * 1024; u.boff = (size_t)pn * 256 * ldb2 + (size_t)h * 1024; }
;         else if (mode == 4) { const int b = pm >> 3, nt_ = pm & 7, h = pn; u.aoff = (size_t)(nt_ * 256) * lda2 + (size_t)h * 1024; u.boff = (size_t)(b * 256) * ldb2 + (size_t)(2048 + h * 512) * 2; }
;         else if (mode == 5) { const int b = pm >> 5; u.aoff = (size_t)pm * 256 * lda2; u.boff = (size_t)(b * 1024 + pn * 256) * ldb2; }
;         else { const int b = pm >> 5; u.aoff = (size_t)pm * 256 * lda2; u.boff = (size_t)(b * 2048 + pn * 256) * ldb2; }
;         return true;
;     }
; template <class Epi>
; __device__ __forceinline__ void gemm_phase(LAS unsigned char* lds, const Gemm g, const Order& S, const Epi& E) {
;     const int tid = threadIdx.x, wid = __builtin_amdgcn_readfirstlane(tid >> 6), lane = tid & 63, wr = wid >> 2, wc = wid & 3, fr = lane & 15, fq = lane >> 4;
;     const int K = g.K, nt = K / BK;
;     unsigned voffA[2], voffB[2];
; #pragma unroll
;     for (int i = 0; i < 2; ++i) { int R, C; stage_rc(tid * 16 + i * 8192, R, C); const int Rb = Epi::PERM ? ((R & ~31) + perm32(R & 31)) : R;
;         voffA[i] = (unsigned)(R * g.lda + C) * 2u; voffB[i] = (unsigned)(Rb * g.ldb + C) * 2u; }
;     ...
;     const char* cA = (const char*)g.A + cur.aoff; const char* cB = (const char*)g.Bt + cur.boff;
;     PG8_STAGE(PG8_SB(0, 0), cB, voffB); PG8_STAGE(PG8_SB(0, 1), cB + hstepB, voffB); PG8_STAGE(PG8_SA(0, 0), cA, voffA); PG8_STAGE(PG8_SA(0, 1), cA + hstepA, voffA);
;     if (wr == 1) PG8_BAR;
.LBB0_1011:
	s_add_u32 s3, s72, 0x14400000
	v_lshrrev_b32_e32 v3, 1, v206
	s_addc_u32 s33, s73, 0
	v_and_b32_e32 v10, 24, v3
	v_lshrrev_b32_e32 v3, 5, v206
	s_add_u32 s38, s72, 0x2f000000
	v_and_b32_e32 v3, 4, v3
	v_bfe_u32 v4, v206, 2, 2
	s_addc_u32 s39, s73, 0
	v_lshlrev_b32_e32 v0, 4, v206
	v_and_b32_e32 v1, 32, v206
	v_bfe_u32 v2, v206, 2, 4
	v_or3_b32 v3, v3, v4, v10
	v_lshrrev_b32_e32 v4, 3, v206
	s_movk_i32 s9, 0x70
	s_add_i32 s5, s8, s5
	v_bitop3_b32 v8, v0, v1, 48 bitop3:0x6c
	v_and_or_b32 v5, v4, s9, v2
	s_movk_i32 s9, 0x60
	v_add_u32_e32 v0, 0x2000, v0
	s_ashr_i32 s8, s5, 31
	v_and_or_b32 v4, v4, s9, v3
	v_lshrrev_b32_e32 v0, 7, v0
	s_movk_i32 s9, 0xf0
	s_lshr_b32 s8, s8, 27
	v_and_or_b32 v2, v0, s9, v2
	s_movk_i32 s9, 0xe0
	s_add_i32 s8, s5, s8
	v_and_or_b32 v0, v0, s9, v3
	s_ashr_i32 s9, s8, 5
	s_and_b32 s8, s8, 0xffe0
	s_sub_i32 s8, s5, s8
	s_bfe_i32 s5, s8, 0x80000
	s_bfe_u32 s5, s5, 0x2000d
	s_add_i32 s11, s8, s5
	s_bfe_i32 s5, s11, 0x80000
	s_and_b32 s11, s11, 0xfc
	s_sub_i32 s8, s8, s11
	s_lshl_b32 s9, s9, 2
	s_sext_i32_i16 s13, s5
	s_sext_i32_i8 s8, s8
	v_and_b32_e32 v9, 64, v206
	s_lshr_b32 s10, s12, 6
	s_add_i32 s55, s9, s8
	s_sub_i32 s55, 0x7f, s55
	s_ashr_i32 s8, s13, 2
	s_lshr_b32 s4, s12, 8
	v_or_b32_e32 v1, v8, v9
	s_lshl_b32 s40, s10, 10
	s_lshr_b32 s5, s13, 2
	s_mul_hi_i32 s9, s8, 0x2c0000
	s_mul_i32 s8, s8, 0x2c0000
	v_lshrrev_b32_e32 v1, 1, v1
	v_mul_u32_u24_e32 v4, 0x1600, v4
	s_add_u32 s34, s38, s8
	v_or_b32_e32 v4, v4, v1
	s_addc_u32 s35, s39, s9
	s_add_i32 s41, s40, 0
	v_lshlrev_b32_e32 v130, 1, v4
	v_mul_u32_u24_e32 v0, 0x1600, v0
	s_add_i32 m0, s41, 0x10000
	v_or_b32_e32 v0, v0, v1
	global_load_lds_dwordx4 v130, s[34:35]
	s_add_i32 m0, s41, 0x12000
	v_lshlrev_b32_e32 v134, 1, v0
	s_add_u32 s8, s34, 0x160000
	global_load_lds_dwordx4 v134, s[34:35]
	s_addc_u32 s9, s35, 0
	s_add_i32 m0, s41, 0x14000
	s_mul_i32 s14, s55, 0x2c0000
	global_load_lds_dwordx4 v130, s[8:9]
	s_add_i32 m0, s41, 0x16000
	v_mul_u32_u24_e32 v11, 0x1600, v5
	s_mul_hi_i32 s11, s55, 0x2c0000
	s_add_u32 s30, s3, s14
	v_or_b32_e32 v5, v1, v11
	v_mul_u32_u24_e32 v12, 0x1600, v2
	s_addc_u32 s31, s33, s11
	s_add_i32 s42, s41, 0x2000
	v_lshlrev_b32_e32 v128, 1, v5
	v_or_b32_e32 v2, v12, v1
	global_load_lds_dwordx4 v134, s[8:9]
	s_mov_b32 m0, s41
	s_add_u32 s8, s30, 0x160000
	v_lshlrev_b32_e32 v132, 1, v2
	global_load_lds_dwordx4 v128, s[30:31]
	s_mov_b32 m0, s42
	s_addc_u32 s9, s31, 0
	s_add_i32 s43, s41, 0x4000
	global_load_lds_dwordx4 v132, s[30:31]
	s_mov_b32 m0, s43
	s_add_i32 s46, s41, 0x6000
	global_load_lds_dwordx4 v128, s[8:9]
	s_mov_b32 m0, s46
	v_mov_b32_e32 v131, 0
	global_load_lds_dwordx4 v132, s[8:9]
	v_mov_b32_e32 v135, v131
	v_mov_b32_e32 v129, v131
	v_mov_b32_e32 v133, v131
	s_cmp_eq_u32 s4, 1
	s_mov_b32 s47, 0
	v_lshl_add_u64 v[6:7], s[34:35], 0, v[130:131]
	v_lshl_add_u64 v[4:5], s[34:35], 0, v[134:135]
	v_lshl_add_u64 v[0:1], s[30:31], 0, v[128:129]
	s_cselect_b64 s[8:9], -1, 0
	s_cmp_lg_u32 s4, 1
	v_lshl_add_u64 v[2:3], s[30:31], 0, v[132:133]
	s_cbranch_scc1 .LBB0_1013
	s_barrier

;     __device__ bool next(int i, Unit& u) const {
;     ...
;         int wgid = (int)L; { const int q = nwg / NXCD, r = nwg % NXCD, xcd = wgid % NXCD, off = wgid / NXCD; wgid = (xcd < r ? xcd * (q + 1) : r * (q + 1) + (xcd - r) * q) + off; }
;         const int nig = WGM * nN, gid = wgid / nig, fm = gid * WGM, gsz = (nM - fm) < WGM ? (nM - fm) : WGM;
;         const int pm = fm + ((wgid % nig) % gsz), pn = (wgid % nig) / gsz;
;         u.pm = pm; u.pn = pn;
;         if (mode == 0) { u.aoff = (size_t)pm * 256 * lda2; u.boff = (size_t)pn * 256 * ldb2; }
.LBB0_1021:
	s_ashr_i32 s22, s24, 3
	s_add_i32 s22, s26, s22
	s_ashr_i32 s23, s22, 31
	s_lshr_b32 s23, s23, 27
	s_add_i32 s23, s22, s23
	s_ashr_i32 s24, s23, 5
	s_lshl_b32 s24, s24, 2
	s_sub_i32 s25, 0x80, s24
	s_min_i32 s25, s25, 4
	s_abs_i32 s26, s25
	v_cvt_f32_u32_e32 v0, s26
	s_sub_i32 s28, 0, s26
	s_andn2_b32 s23, s23, 31
	s_sub_i32 s22, s22, s23
	v_rcp_iflag_f32_e32 v0, v0
	s_abs_i32 s23, s22
	s_xor_b32 s27, s22, s25
	s_ashr_i32 s27, s27, 31
	v_mul_f32_e32 v0, 0x4f7ffffe, v0
	v_cvt_u32_f32_e32 v0, v0
	s_nop 0
	v_readfirstlane_b32 s29, v0
	s_mul_i32 s28, s28, s29
	s_mul_hi_u32 s28, s29, s28
	s_add_i32 s29, s29, s28
	s_mul_hi_u32 s28, s23, s29
	s_mul_i32 s29, s28, s26
	s_sub_i32 s23, s23, s29
	s_add_i32 s36, s28, 1
	s_sub_i32 s29, s23, s26
	s_cmp_ge_u32 s23, s26
	s_cselect_b32 s28, s36, s28
	s_cselect_b32 s23, s29, s23
	s_add_i32 s29, s28, 1
	s_cmp_ge_u32 s23, s26
	s_cselect_b32 s23, s29, s28
	s_xor_b32 s23, s23, s27
	s_sub_i32 s53, s23, s27
	s_mul_i32 s23, s53, s25
	s_sub_i32 s22, s22, s23
	s_add_i32 s54, s24, s22
	s_sub_i32 s54, 0x7f, s54
	s_mul_hi_i32 s23, s54, 0x2c0000
	s_mul_i32 s22, s54, 0x2c0000
	s_mul_hi_i32 s25, s53, 0x2c0000
	s_mul_i32 s24, s53, 0x2c0000
